# v23 + one static s_setprio 1 for waves 4-7 during the layer-A attention phase (breaks the lockstep of the two waves per SIMD)
# speedup vs baseline: 1.0066x; 1.0001x over previous
_Z8yoco_fwd4Args:
	s_load_dwordx2 s[4:5], s[0:1], 0xd0
	s_load_dword s3, s[0:1], 0xd8
	s_add_u32 s66, s0, 0xd0
	s_addc_u32 s67, s1, 0
	v_and_b32_e32 v212, 0x3ff, v0
	v_lshrrev_b32_e32 v1, 8, v212
	s_nop 1
	v_readfirstlane_b32 s98, v1
	s_waitcnt lgkmcnt(0)
	v_writelane_b32 v252, s4, 0
	s_mov_b32 s53, 0
	s_nop 0
	v_writelane_b32 v252, s5, 1
	v_cmp_eq_u32_e64 s[4:5], 0, v212
	s_mov_b64 s[20:21], exec
	s_nop 0
	v_writelane_b32 v252, s4, 2
	s_nop 1
	v_writelane_b32 v252, s5, 3
	s_and_b64 s[4:5], s[20:21], s[4:5]
	s_mov_b64 exec, s[4:5]
	s_cbranch_execz .LBB0_2
	s_load_dwordx16 s[4:19], s[0:1], 0x0
	s_add_i32 s22, 0, 0x23f00
	s_load_dwordx16 s[36:51], s[0:1], 0x40
	v_mov_b32_e32 v1, s22
	s_add_i32 s22, 0, 0x23f70
	s_waitcnt lgkmcnt(0)
	v_mov_b32_e32 v2, s4
	v_mov_b32_e32 v3, s5
	v_mov_b32_e32 v4, s6
	v_mov_b32_e32 v5, s7
	s_add_i32 s4, 0, 0x23f10
	ds_write_b128 v1, v[2:5]
	v_mov_b32_e32 v2, s8
	v_mov_b32_e32 v3, s9
	v_mov_b32_e32 v4, s10
	v_mov_b32_e32 v5, s11
	v_mov_b32_e32 v1, s4
	s_add_i32 s4, 0, 0x23f20
	ds_write_b128 v1, v[2:5]
	v_mov_b32_e32 v2, s12
	v_mov_b32_e32 v3, s13
	v_mov_b32_e32 v4, s14
	v_mov_b32_e32 v5, s15
	v_mov_b32_e32 v1, s4
	s_add_i32 s4, 0, 0x23f30
	ds_write_b128 v1, v[2:5]
	v_mov_b32_e32 v2, s16
	v_mov_b32_e32 v3, s17
	v_mov_b32_e32 v4, s18
	v_mov_b32_e32 v5, s19
	v_mov_b32_e32 v1, s4
	s_add_i32 s4, 0, 0x23f40
	ds_write_b128 v1, v[2:5]
	v_mov_b32_e32 v2, s36
	v_mov_b32_e32 v3, s37
	v_mov_b32_e32 v4, s38
	v_mov_b32_e32 v5, s39
	v_mov_b32_e32 v1, s4
	s_add_i32 s4, 0, 0x23f50
	ds_write_b128 v1, v[2:5]
	v_mov_b32_e32 v2, s40
	v_mov_b32_e32 v3, s41
	v_mov_b32_e32 v4, s42
	v_mov_b32_e32 v5, s43
	v_mov_b32_e32 v1, s4
	s_add_i32 s4, 0, 0x23f60
	ds_write_b128 v1, v[2:5]
	v_mov_b32_e32 v1, s4
	s_load_dwordx16 s[4:19], s[0:1], 0x80
	v_mov_b32_e32 v2, s44
	v_mov_b32_e32 v3, s45
	v_mov_b32_e32 v4, s46
	v_mov_b32_e32 v5, s47
	ds_write_b128 v1, v[2:5]
	v_mov_b32_e32 v2, s48
	v_mov_b32_e32 v3, s49
	v_mov_b32_e32 v4, s50
	v_mov_b32_e32 v5, s51
	v_mov_b32_e32 v1, s22
	ds_write_b128 v1, v[2:5]
	s_waitcnt lgkmcnt(0)
	v_mov_b32_e32 v2, s4
	s_add_i32 s4, 0, 0x23f80
	v_mov_b32_e32 v3, s5
	v_mov_b32_e32 v4, s6
	v_mov_b32_e32 v5, s7
	v_mov_b32_e32 v1, s4
	s_add_i32 s4, 0, 0x23f90
	ds_write_b128 v1, v[2:5]
	v_mov_b32_e32 v2, s8
	v_mov_b32_e32 v3, s9
	v_mov_b32_e32 v4, s10
	v_mov_b32_e32 v5, s11
	v_mov_b32_e32 v1, s4
	s_add_i32 s4, 0, 0x23fa0
	ds_write_b128 v1, v[2:5]
	v_mov_b32_e32 v2, s12
	v_mov_b32_e32 v3, s13
	v_mov_b32_e32 v4, s14
	v_mov_b32_e32 v5, s15
	v_mov_b32_e32 v1, s4
	s_add_i32 s4, 0, 0x23fb0
	ds_write_b128 v1, v[2:5]
	v_mov_b32_e32 v2, s16
	v_mov_b32_e32 v3, s17
	v_mov_b32_e32 v4, s18
	v_mov_b32_e32 v5, s19
	v_mov_b32_e32 v1, s4
	ds_write_b128 v1, v[2:5]
	s_add_i32 s4, 0, 0x23fc0
	v_mov_b32_e32 v2, 0
	v_mov_b32_e32 v3, v2
	v_mov_b32_e32 v1, s4
	ds_write_b64 v1, v[2:3]

.LBB0_614:
	s_and_b64 vcc, exec, s[4:5]
	s_cbranch_vccz .LBB0_643
	s_cmpk_gt_i32 s79, 0x41f
	s_cbranch_scc1 .LBB0_643
	s_cmp_eq_u32 s98, 0
	s_cbranch_scc1 .Lmy_prio_a
	s_setprio 1
.Lmy_prio_a:
	v_readlane_b32 s4, v252, 58
	v_readlane_b32 s5, v252, 59
	s_add_u32 s3, s4, 0x175c0000
	s_addc_u32 s14, s5, 0
	s_add_u32 s15, s4, 0x18600000
	s_addc_u32 s16, s5, 0
	s_add_u32 s4, s4, 0x1998c000
	v_readlane_b32 s7, v252, 62
	s_addc_u32 s5, s5, 0
	s_lshl_b32 s6, s7, 7
	s_and_b32 s18, s6, 0x180
	s_mul_i32 s6, s7, 0x2200
	s_lshl_b32 s17, s7, 3
	s_add_i32 s19, s6, 0
	s_not_b32 s6, s79
	s_andn2_b32 s17, s17, 31
	s_add_i32 s20, s73, s6
	v_readlane_b32 s6, v252, 13
	v_readlane_b32 s10, v252, 46
	v_readlane_b32 s11, v252, 47
	s_add_u32 s6, s6, s10
	v_readlane_b32 s7, v252, 14
	s_addc_u32 s7, s7, s11
	v_readlane_b32 s8, v252, 15
	s_add_u32 s8, s8, s10
	v_readlane_b32 s9, v252, 16
	v_lshl_add_u32 v185, v184, 4, 0
	v_mul_u32_u24_e32 v186, 0x110, v177
	v_lshlrev_b32_e32 v187, 2, v184
	v_mul_u32_u24_e32 v188, 0x90, v177
	s_addc_u32 s9, s9, s11
	s_mov_b32 s21, 0
	s_mov_b32 s13, s79
	s_mov_b32 s34, 0x3e0293ee
	s_mov_b64 s[36:37], 0x10000
	s_branch .LBB0_618

.LBB0_1556:
	s_setprio 0
	s_movk_i32 s47, 0x1580
	s_movk_i32 s49, 0x4140
	s_cbranch_execz .LBB0_645
	s_branch .LBB0_668
